# grid barrier: XCD leader bumps the generation word before issuing its own acquire invalidate
# speedup vs baseline: 1.0009x; 1.0009x over previous
; __device__ __forceinline__ unsigned xb_ld(unsigned* p)              { return __hip_atomic_load(p, __ATOMIC_RELAXED, __HIP_MEMORY_SCOPE_AGENT); }
; __device__ __forceinline__ unsigned xb_add(unsigned* p, unsigned v) { return __hip_atomic_fetch_add(p, v, __ATOMIC_RELAXED, __HIP_MEMORY_SCOPE_AGENT); }
; #define XB_SPIN(cond, bar) do { unsigned _sp = 0; while (cond) { __builtin_amdgcn_s_sleep(1); \
;     if ((++_sp & 255u) == 0u) { if (xb_ld(&(bar)[XB_TMO])) break; if (_sp > XB_SPIN_CAP) { atomicAdd(&(bar)[XB_TMO], 1u); break; } } } } while (0)
; __device__ __forceinline__ void xcd_barrier(const XcdBarrier& b) {
;     ...
;             const unsigned og = xb_add(&bar[XB_TOP], 1u);
;             const unsigned tg = og / nx;
;             if (og + 1u == (tg + 1u) * nx) xb_add(&bar[XB_TOPGEN], 1u);
;             else XB_SPIN(xb_ld(&bar[XB_TOPGEN]) == tg, bar);
;             __builtin_amdgcn_fence(__ATOMIC_ACQUIRE, "agent");
;             xb_add(&bar[XB_XGEN(b.x)], 1u);
;             asm volatile("s_waitcnt vmcnt(0)" ::: "memory");
.LBB0_1795:
	s_or_b64 exec, exec, s[12:13]
	s_mov_b64 s[12:13], exec
	v_mbcnt_lo_u32_b32 v0, s12, 0
	v_mbcnt_hi_u32_b32 v0, s13, v0
	v_cmp_eq_u32_e32 vcc, 0, v0
	s_waitcnt vmcnt(0)
	s_and_saveexec_b64 s[14:15], vcc
	s_cbranch_execnz .LBB0_1796
	s_or_b64 exec, exec, s[14:15]
	buffer_inv sc1
	s_getpc_b64 s[98:99]

; __device__ __forceinline__ unsigned xb_add(unsigned* p, unsigned v) { return __hip_atomic_fetch_add(p, v, __ATOMIC_RELAXED, __HIP_MEMORY_SCOPE_AGENT); }
; __device__ __forceinline__ void xcd_barrier(const XcdBarrier& b) {
;     ...
;             __builtin_amdgcn_fence(__ATOMIC_ACQUIRE, "agent");
;             xb_add(&bar[XB_XGEN(b.x)], 1u);
;             asm volatile("s_waitcnt vmcnt(0)" ::: "memory");
.LBB0_1796:
	s_bcnt1_i32_b64 s2, s[12:13]
	v_readlane_b32 s10, v232, 49
	v_mov_b32_e32 v0, s2
	v_readlane_b32 s11, v232, 50
	s_nop 4
	global_atomic_add v13, v0, s[10:11]
	buffer_inv sc1
	s_getpc_b64 s[98:99]
